# top-k selection as exact radix select (ballot/popcount threshold search + mbcnt tie order) instead of O(n^2) rank counting
# speedup vs baseline: 1.0237x; 1.0126x over previous
; __device__ __forceinline__ float af_sigmoid(float x) { return 1.f / (1.f + __expf(-x)); }
; __device__ __forceinline__ void attn_fast(const Ptrs& P, LAS unsigned char* lds, int G, int bid) {
;     ...
;             for (int ct = 0; ct < 2; ++ct) { int _ln; asm volatile("v_mov_b32 %0, %1" : "=v"(_ln) : "v"(lane));
;                 const int fr_ = _ln & 15, fq_ = _ln >> 4, hh_ = fr_ & 3;
;                 const size_t row = (size_t)b * SEQ + 64 * qb + 8 * w + 4 * ct + (fr_ >> 2);
;                 const float g0 = af_sigmoid((float)U[row * DINP + OFF_GL + (4 * g + hh_) * 3 + 0]);
;                 af_write(Y, row, (4 * g + hh_) * 128 + 4 * fq_, o[ct], 64.f * g0, false); }
;             __syncthreads();
.LBB0_566:
	s_lshl_b32 s1, s54, 2
	v_mov_b32 v106, v172
	s_waitcnt lgkmcnt(0)
	v_mov_b64_e32 v[102:103], s[18:19]
	v_lshrrev_b32_e32 v2, 2, v106
	v_and_or_b32 v4, v2, 3, s37
	v_and_or_b32 v107, v106, 3, s1
	v_mul_u32_u24_e32 v2, 3, v107
	v_mad_u64_u32 v[104:105], s[6:7], v4, s86, v[102:103]
	v_mad_i32_i24 v105, s95, v205, v105
	v_lshlrev_b32_e32 v2, 1, v2
	v_lshl_add_u64 v[104:105], v[104:105], 0, v[2:3]
	v_add_co_u32_e32 v104, vcc, s93, v104
	v_mov_b32_e32 v5, s95
	s_nop 0
	v_addc_co_u32_e32 v105, vcc, 0, v105, vcc
	global_load_ushort v2, v[104:105], off offset:3072
	v_ashrrev_i32_e32 v104, 2, v106
	v_and_b32_e32 v104, -4, v104
	v_lshl_add_u32 v104, v107, 7, v104
	v_lshlrev_b64 v[4:5], 11, v[4:5]
	v_lshl_add_u64 v[4:5], s[20:21], 0, v[4:5]
	v_ashrrev_i32_e32 v105, 31, v104
	v_lshl_add_u64 v[4:5], v[104:105], 1, v[4:5]
	s_mul_i32 s3, s95, 0x2e00
	s_mov_b32 s16, s85
	s_waitcnt vmcnt(0)
	v_cvt_f32_f16_e32 v2, v2
	v_mul_f32_e32 v2, 0xbfb8aa3b, v2
	v_exp_f32_e32 v2, v2
	s_nop 0
	v_add_f32_e32 v2, 1.0, v2
	v_div_scale_f32 v106, s[6:7], v2, v2, 1.0
	v_rcp_f32_e32 v107, v106
	v_div_scale_f32 v104, vcc, 1.0, v2, 1.0
	v_fma_f32 v105, -v106, v107, 1.0
	v_fmac_f32_e32 v107, v105, v107
	v_mul_f32_e32 v105, v104, v107
	v_fma_f32 v108, -v106, v105, v104
	v_fmac_f32_e32 v105, v108, v107
	v_fma_f32 v104, -v106, v105, v104
	v_div_fmas_f32 v104, v104, v107, v105
	v_div_fixup_f32 v2, v104, v2, 1.0
	v_mul_f32_e32 v2, 0x42800000, v2
	v_pk_mul_f32 v[100:101], v[100:101], v[2:3] op_sel_hi:[1,0]
	v_pk_mul_f32 v[98:99], v[98:99], v[2:3] op_sel_hi:[1,0]
	v_pk_mul_f32 v[72:73], v[72:73], v[2:3] op_sel_hi:[1,0]
	v_pk_mul_f32 v[70:71], v[70:71], v[2:3] op_sel_hi:[1,0]
	v_pk_mul_f32 v[96:97], v[96:97], v[2:3] op_sel_hi:[1,0]
	v_pk_mul_f32 v[94:95], v[94:95], v[2:3] op_sel_hi:[1,0]
	v_pk_mul_f32 v[92:93], v[92:93], v[2:3] op_sel_hi:[1,0]
	v_pk_mul_f32 v[90:91], v[90:91], v[2:3] op_sel_hi:[1,0]
	v_pk_mul_f32 v[88:89], v[88:89], v[2:3] op_sel_hi:[1,0]
	v_pk_mul_f32 v[86:87], v[86:87], v[2:3] op_sel_hi:[1,0]
	v_pk_mul_f32 v[84:85], v[84:85], v[2:3] op_sel_hi:[1,0]
	v_pk_mul_f32 v[82:83], v[82:83], v[2:3] op_sel_hi:[1,0]
	v_pk_mul_f32 v[80:81], v[80:81], v[2:3] op_sel_hi:[1,0]
	v_pk_mul_f32 v[78:79], v[78:79], v[2:3] op_sel_hi:[1,0]
	v_pk_mul_f32 v[76:77], v[76:77], v[2:3] op_sel_hi:[1,0]
	v_pk_mul_f32 v[74:75], v[74:75], v[2:3] op_sel_hi:[1,0]
	v_cvt_pk_f16_f32 v101, v100, v101
	v_cvt_pk_f16_f32 v100, v98, v99
	v_cvt_pk_f16_f32 v73, v72, v73
	v_cvt_pk_f16_f32 v72, v70, v71
	v_cvt_pk_f16_f32 v97, v96, v97
	v_cvt_pk_f16_f32 v96, v94, v95
	v_cvt_pk_f16_f32 v93, v92, v93
	v_cvt_pk_f16_f32 v92, v90, v91
	v_cvt_pk_f16_f32 v89, v88, v89
	v_cvt_pk_f16_f32 v88, v86, v87
	v_cvt_pk_f16_f32 v85, v84, v85
	v_cvt_pk_f16_f32 v84, v82, v83
	v_cvt_pk_f16_f32 v81, v80, v81
	v_cvt_pk_f16_f32 v80, v78, v79
	v_cvt_pk_f16_f32 v77, v76, v77
	v_cvt_pk_f16_f32 v76, v74, v75
	global_store_dwordx2 v[4:5], v[100:101], off
	global_store_dwordx2 v[4:5], v[96:97], off offset:32
	global_store_dwordx2 v[4:5], v[92:93], off offset:64
	global_store_dwordx2 v[4:5], v[88:89], off offset:96
	global_store_dwordx2 v[4:5], v[84:85], off offset:128
	global_store_dwordx2 v[4:5], v[80:81], off offset:160
	global_store_dwordx2 v[4:5], v[76:77], off offset:192
	global_store_dwordx2 v[4:5], v[72:73], off offset:224
	v_mov_b32 v72, v172
	v_mov_b32_e32 v5, s95
	v_lshrrev_b32_e32 v2, 2, v72
	v_and_or_b32 v73, v72, 3, s1
	v_and_or_b32 v4, v2, 3, s28
	v_mul_u32_u24_e32 v2, 3, v73
	v_mad_u64_u32 v[70:71], s[6:7], v4, s86, v[102:103]
	v_lshlrev_b32_e32 v2, 1, v2
	v_add_u32_e32 v71, s3, v71
	v_lshl_add_u64 v[70:71], v[70:71], 0, v[2:3]
	v_add_co_u32_e32 v70, vcc, s93, v70
	v_lshlrev_b64 v[4:5], 11, v[4:5]
	s_nop 0
	v_addc_co_u32_e32 v71, vcc, 0, v71, vcc
	global_load_ushort v2, v[70:71], off offset:3072
	v_ashrrev_i32_e32 v70, 2, v72
	v_and_b32_e32 v70, -4, v70
	v_lshl_add_u32 v70, v73, 7, v70
	v_lshl_add_u64 v[4:5], s[20:21], 0, v[4:5]
	v_ashrrev_i32_e32 v71, 31, v70
	v_lshl_add_u64 v[4:5], v[70:71], 1, v[4:5]
	s_mov_b32 s3, 0
	s_waitcnt vmcnt(0)
	v_cvt_f32_f16_e32 v2, v2
	v_mul_f32_e32 v2, 0xbfb8aa3b, v2
	v_exp_f32_e32 v2, v2
	s_nop 0
	v_add_f32_e32 v2, 1.0, v2
	v_div_scale_f32 v72, s[6:7], v2, v2, 1.0
	v_rcp_f32_e32 v73, v72
	v_div_scale_f32 v70, vcc, 1.0, v2, 1.0
	v_fma_f32 v71, -v72, v73, 1.0
	v_fmac_f32_e32 v73, v71, v73
	v_mul_f32_e32 v71, v70, v73
	v_fma_f32 v74, -v72, v71, v70
	v_fmac_f32_e32 v71, v74, v73
	v_fma_f32 v70, -v72, v71, v70
	v_div_fmas_f32 v70, v70, v73, v71
	v_div_fixup_f32 v2, v70, v2, 1.0
	v_mul_f32_e32 v2, 0x42800000, v2
	v_pk_mul_f32 v[68:69], v[68:69], v[2:3] op_sel_hi:[1,0]
	v_pk_mul_f32 v[66:67], v[66:67], v[2:3] op_sel_hi:[1,0]
	v_pk_mul_f32 v[64:65], v[64:65], v[2:3] op_sel_hi:[1,0]
	v_pk_mul_f32 v[62:63], v[62:63], v[2:3] op_sel_hi:[1,0]
	v_pk_mul_f32 v[60:61], v[60:61], v[2:3] op_sel_hi:[1,0]
	v_pk_mul_f32 v[58:59], v[58:59], v[2:3] op_sel_hi:[1,0]
	v_pk_mul_f32 v[56:57], v[56:57], v[2:3] op_sel_hi:[1,0]
	v_pk_mul_f32 v[54:55], v[54:55], v[2:3] op_sel_hi:[1,0]
	v_pk_mul_f32 v[52:53], v[52:53], v[2:3] op_sel_hi:[1,0]
	v_pk_mul_f32 v[50:51], v[50:51], v[2:3] op_sel_hi:[1,0]
	v_pk_mul_f32 v[48:49], v[48:49], v[2:3] op_sel_hi:[1,0]
	v_pk_mul_f32 v[46:47], v[46:47], v[2:3] op_sel_hi:[1,0]
	v_pk_mul_f32 v[44:45], v[44:45], v[2:3] op_sel_hi:[1,0]
	v_pk_mul_f32 v[42:43], v[42:43], v[2:3] op_sel_hi:[1,0]
	v_pk_mul_f32 v[40:41], v[40:41], v[2:3] op_sel_hi:[1,0]
	v_pk_mul_f32 v[38:39], v[38:39], v[2:3] op_sel_hi:[1,0]
	v_cvt_pk_f16_f32 v69, v68, v69
	v_cvt_pk_f16_f32 v68, v66, v67
	v_cvt_pk_f16_f32 v65, v64, v65
	v_cvt_pk_f16_f32 v64, v62, v63
	v_cvt_pk_f16_f32 v61, v60, v61
	v_cvt_pk_f16_f32 v60, v58, v59
	v_cvt_pk_f16_f32 v57, v56, v57
	v_cvt_pk_f16_f32 v56, v54, v55
	v_cvt_pk_f16_f32 v53, v52, v53
	v_cvt_pk_f16_f32 v52, v50, v51
	v_cvt_pk_f16_f32 v49, v48, v49
	v_cvt_pk_f16_f32 v48, v46, v47
	v_cvt_pk_f16_f32 v45, v44, v45
	v_cvt_pk_f16_f32 v44, v42, v43
	v_cvt_pk_f16_f32 v41, v40, v41
	v_cvt_pk_f16_f32 v40, v38, v39
	global_store_dwordx2 v[4:5], v[68:69], off
	global_store_dwordx2 v[4:5], v[64:65], off offset:32
	global_store_dwordx2 v[4:5], v[60:61], off offset:64
	global_store_dwordx2 v[4:5], v[56:57], off offset:96
	global_store_dwordx2 v[4:5], v[52:53], off offset:128
	global_store_dwordx2 v[4:5], v[48:49], off offset:160
	global_store_dwordx2 v[4:5], v[44:45], off offset:192
	global_store_dwordx2 v[4:5], v[40:41], off offset:224
	s_barrier
	s_mov_b32 s3, 0
; #define LAS __attribute__((address_space(3)))
; __device__ __forceinline__ void attn_fast(const Ptrs& P, LAS unsigned char* lds, int G, int bid) {
;     ...
; #pragma unroll 1
;             for (int ql = 0; ql < 8; ql += 2) {
;                 LAS float* rowa = IMP + ql * 132; LAS float* rowb = rowa + 132;
;                 float a0, a1, b0, b1;
;                 { const int j = lane; const bool valid = j <= qb, forced = (j == 0) || (j == qb) || (j == qb - 1); const float bonus = forced ? 1.0e4f : 0.f;
;                   const float va = rowa[j], vb = rowb[j]; a0 = valid ? va + bonus : -1.f; b0 = valid ? vb + bonus : -1.f; rowa[j] = a0; rowb[j] = b0; }
;                 { const int j = lane + 64; const bool valid = j <= qb, forced = (j == 0) || (j == qb) || (j == qb - 1); const float bonus = forced ? 1.0e4f : 0.f;
;                   const float va = rowa[j], vb = rowb[j]; a1 = valid ? va + bonus : -1.f; b1 = valid ? vb + bonus : -1.f; rowa[j] = a1; rowb[j] = b1; }
;                 int ra0 = 0, ra1 = 0, rb0 = 0, rb1 = 0;
;                 for (int j4 = 0; j4 <= qb; j4 += 4) { const f32x4 xa = *(const LAS f32x4*)(rowa + j4); const f32x4 xb = *(const LAS f32x4*)(rowb + j4);
; #pragma unroll
;                     for (int e = 0; e < 4; ++e) { const int j = j4 + e;
;                         ra0 += (xa[e] > a0 || (xa[e] == a0 && j < lane)) ? 1 : 0; ra1 += (xa[e] > a1 || (xa[e] == a1 && j < lane + 64)) ? 1 : 0;
;                         rb0 += (xb[e] > b0 || (xb[e] == b0 && j < lane)) ? 1 : 0; rb1 += (xb[e] > b1 || (xb[e] == b1 && j < lane + 64)) ? 1 : 0; } }
;                 const unsigned long long alo = __ballot(ra0 < 16 && lane <= qb), ahi = __ballot(ra1 < 16 && lane + 64 <= qb);
;                 const unsigned long long blo = __ballot(rb0 < 16 && lane <= qb), bhi = __ballot(rb1 < 16 && lane + 64 <= qb);
;                 if (lane == 0) { LAS unsigned* sp = SELM + (8 * w + ql) * 4; sp[0] = (unsigned)alo; sp[1] = (unsigned)(alo >> 32); sp[2] = (unsigned)ahi; sp[3] = (unsigned)(ahi >> 32);
;                                  sp[4] = (unsigned)blo; sp[5] = (unsigned)(blo >> 32); sp[6] = (unsigned)bhi; sp[7] = (unsigned)(bhi >> 32); }
;             }
.Ltk_pair:
	s_cmp_lt_i32 s94, 16
	s_cbranch_scc0 .Ltk_radix
	s_mov_b64 s[98:99], s[44:45]
	s_mov_b64 s[100:101], s[46:47]
	s_mov_b64 s[6:7], s[44:45]
	s_mov_b64 s[8:9], s[46:47]
	s_branch .Ltk_store
.Ltk_radix:
	s_mul_i32 s6, s3, 0x210
	s_add_i32 s6, s66, s6
	v_lshl_add_u32 v40, v172, 2, s6
	ds_read2st64_b32 v[4:5], v40 offset1:1
	ds_read2_b32 v[38:39], v40 offset0:132 offset1:196
	s_waitcnt lgkmcnt(0)
	v_add_f32_e32 v4, v210, v4
	v_add_f32_e32 v38, v210, v38
	v_add_f32_e32 v5, v211, v5
	v_add_f32_e32 v39, v211, v39
	v_add_u32_e32 v4, 1, v4
	v_add_u32_e32 v38, 1, v38
	v_add_u32_e32 v5, 1, v5
	v_add_u32_e32 v39, 1, v39
	v_cndmask_b32_e64 v4, 0, v4, s[44:45]
	v_cndmask_b32_e64 v38, 0, v38, s[44:45]
	v_cndmask_b32_e64 v5, 0, v5, s[46:47]
	v_cndmask_b32_e64 v39, 0, v39, s[46:47]
	s_mov_b32 s16, 0
	s_mov_b32 s17, 0
	s_mov_b32 s22, 0x40000000
.Ltk_bit:
	s_or_b32 s52, s16, s22
	s_or_b32 s53, s17, s22
	v_cmp_le_u32_e64 s[6:7], s52, v4
	v_cmp_le_u32_e64 s[8:9], s52, v5
	v_cmp_le_u32_e64 s[12:13], s53, v38
	v_cmp_le_u32_e32 vcc, s53, v39
	s_bcnt1_i32_b64 s6, s[6:7]
	s_bcnt1_i32_b64 s8, s[8:9]
	s_bcnt1_i32_b64 s12, s[12:13]
	s_bcnt1_i32_b64 s13, vcc
	s_add_i32 s6, s6, s8
	s_add_i32 s12, s12, s13
	s_cmp_gt_u32 s6, 15
	s_cselect_b32 s16, s52, s16
	s_cmp_gt_u32 s12, 15
	s_cselect_b32 s17, s53, s17
	s_lshr_b32 s22, s22, 1
	s_cmp_lg_u32 s22, 0
	s_cbranch_scc1 .Ltk_bit
	v_cmp_lt_u32_e64 s[98:99], s16, v4
	v_cmp_lt_u32_e64 s[100:101], s16, v5
	v_cmp_eq_u32_e64 s[12:13], s16, v4
	v_cmp_eq_u32_e32 vcc, s16, v5
	s_bcnt1_i32_b64 s22, s[98:99]
	s_bcnt1_i32_b64 s52, s[100:101]
	s_add_i32 s22, s22, s52
	s_sub_i32 s22, 16, s22
	v_mbcnt_lo_u32_b32 v41, s12, 0
	v_mbcnt_hi_u32_b32 v41, s13, v41
	s_bcnt1_i32_b64 s52, s[12:13]
	v_mbcnt_lo_u32_b32 v42, vcc_lo, 0
	v_mbcnt_hi_u32_b32 v42, vcc_hi, v42
	v_add_u32_e32 v42, s52, v42
	v_cmp_gt_u32_e64 s[52:53], s22, v41
	s_and_b64 s[12:13], s[12:13], s[52:53]
	s_or_b64 s[98:99], s[98:99], s[12:13]
	v_cmp_gt_u32_e64 s[52:53], s22, v42
	s_and_b64 s[52:53], vcc, s[52:53]
	s_or_b64 s[100:101], s[100:101], s[52:53]
	s_and_b64 s[98:99], s[98:99], s[44:45]
	s_and_b64 s[100:101], s[100:101], s[46:47]
	v_cmp_lt_u32_e64 s[6:7], s17, v38
	v_cmp_lt_u32_e64 s[8:9], s17, v39
	v_cmp_eq_u32_e64 s[12:13], s17, v38
	v_cmp_eq_u32_e32 vcc, s17, v39
	s_bcnt1_i32_b64 s22, s[6:7]
	s_bcnt1_i32_b64 s52, s[8:9]
	s_add_i32 s22, s22, s52
	s_sub_i32 s22, 16, s22
	v_mbcnt_lo_u32_b32 v41, s12, 0
	v_mbcnt_hi_u32_b32 v41, s13, v41
	s_bcnt1_i32_b64 s52, s[12:13]
	v_mbcnt_lo_u32_b32 v42, vcc_lo, 0
	v_mbcnt_hi_u32_b32 v42, vcc_hi, v42
	v_add_u32_e32 v42, s52, v42
	v_cmp_gt_u32_e64 s[52:53], s22, v41
	s_and_b64 s[12:13], s[12:13], s[52:53]
	s_or_b64 s[6:7], s[6:7], s[12:13]
	v_cmp_gt_u32_e64 s[52:53], s22, v42
	s_and_b64 s[52:53], vcc, s[52:53]
	s_or_b64 s[8:9], s[8:9], s[52:53]
	s_and_b64 s[6:7], s[6:7], s[44:45]
	s_and_b64 s[8:9], s[8:9], s[46:47]
.Ltk_store:
	s_add_i32 s22, s3, s70
	s_lshl_b32 s22, s22, 4
	s_add_i32 s22, s22, 0x20400
	v_mov_b32_e32 v2, s22
	v_mov_b32_e32 v40, s98
	v_mov_b32_e32 v41, s99
	v_mov_b32_e32 v42, s100
	v_mov_b32_e32 v43, s101
	v_mov_b32_e32 v44, s6
	v_mov_b32_e32 v45, s7
	v_mov_b32_e32 v46, s8
	v_mov_b32_e32 v47, s9
	s_and_saveexec_b64 s[12:13], s[4:5]
	ds_write_b128 v2, v[40:43]
	ds_write_b128 v2, v[44:47] offset:16
	s_or_b64 exec, exec, s[12:13]
	s_add_i32 s3, s3, 2
	s_cmp_lt_u32 s3, 8
	s_cbranch_scc1 .Ltk_pair

; __global__ void __launch_bounds__(NTHR, 2) mega(Args args) {
;     extern __shared__ __attribute__((aligned(16))) unsigned char lds_raw[];
	.amdhsa_kernel _Z4mega4Args
		.amdhsa_group_segment_fixed_size 0
		.amdhsa_private_segment_fixed_size 0
		.amdhsa_kernarg_size 448
		.amdhsa_user_sgpr_count 2
		.amdhsa_user_sgpr_dispatch_ptr 0
		.amdhsa_user_sgpr_queue_ptr 0
		.amdhsa_user_sgpr_kernarg_segment_ptr 1
		.amdhsa_user_sgpr_dispatch_id 0
		.amdhsa_user_sgpr_kernarg_preload_length 0
		.amdhsa_user_sgpr_kernarg_preload_offset 0
		.amdhsa_user_sgpr_private_segment_size 0
		.amdhsa_uses_dynamic_stack 0
		.amdhsa_enable_private_segment 0
		.amdhsa_system_sgpr_workgroup_id_x 1
		.amdhsa_system_sgpr_workgroup_id_y 0
		.amdhsa_system_sgpr_workgroup_id_z 0
		.amdhsa_system_sgpr_workgroup_info 0
		.amdhsa_system_vgpr_workitem_id 2
		.amdhsa_next_free_vgpr 256
		.amdhsa_next_free_sgpr 102
		.amdhsa_accum_offset 256
		.amdhsa_reserve_vcc 1
		.amdhsa_float_round_mode_32 0
		.amdhsa_float_round_mode_16_64 0
		.amdhsa_float_denorm_mode_32 3
		.amdhsa_float_denorm_mode_16_64 3
		.amdhsa_dx10_clamp 1
		.amdhsa_ieee_mode 1
		.amdhsa_fp16_overflow 0
		.amdhsa_tg_split 0
		.amdhsa_exception_fp_ieee_invalid_op 0
		.amdhsa_exception_fp_denorm_src 0
		.amdhsa_exception_fp_ieee_div_zero 0
		.amdhsa_exception_fp_ieee_overflow 0
		.amdhsa_exception_fp_ieee_underflow 0
		.amdhsa_exception_fp_ieee_inexact 0
		.amdhsa_exception_int_div_zero 0
	.end_amdhsa_kernel

; __global__ void __launch_bounds__(NTHR, 2) mega(Args args) {
;     extern __shared__ __attribute__((aligned(16))) unsigned char lds_raw[];
amdhsa.kernels:
  - .agpr_count:     0
    .args:
      - .offset:         0
        .size:           192
        .value_kind:     by_value
      - .offset:         192
        .size:           4
        .value_kind:     hidden_block_count_x
      - .offset:         196
        .size:           4
        .value_kind:     hidden_block_count_y
      - .offset:         200
        .size:           4
        .value_kind:     hidden_block_count_z
      - .offset:         204
        .size:           2
        .value_kind:     hidden_group_size_x
      - .offset:         206
        .size:           2
        .value_kind:     hidden_group_size_y
      - .offset:         208
        .size:           2
        .value_kind:     hidden_group_size_z
      - .offset:         210
        .size:           2
        .value_kind:     hidden_remainder_x
      - .offset:         212
        .size:           2
        .value_kind:     hidden_remainder_y
      - .offset:         214
        .size:           2
        .value_kind:     hidden_remainder_z
      - .offset:         232
        .size:           8
        .value_kind:     hidden_global_offset_x
      - .offset:         240
        .size:           8
        .value_kind:     hidden_global_offset_y
      - .offset:         248
        .size:           8
        .value_kind:     hidden_global_offset_z
      - .offset:         256
        .size:           2
        .value_kind:     hidden_grid_dims
      - .offset:         280
        .size:           8
        .value_kind:     hidden_multigrid_sync_arg
      - .offset:         312
        .size:           4
        .value_kind:     hidden_dynamic_lds_size
    .group_segment_fixed_size: 0
    .kernarg_segment_align: 8
    .kernarg_segment_size: 448
    .language:       OpenCL C
    .language_version:
      - 2
      - 0
    .max_flat_workgroup_size: 512
    .name:           _Z4mega4Args
    .private_segment_fixed_size: 0
    .sgpr_count:     108
    .sgpr_spill_count: 13
    .symbol:         _Z4mega4Args.kd
    .uniform_work_group_size: 1
    .uses_dynamic_stack: false
    .vgpr_count:     256
    .vgpr_spill_count: 0
    .wavefront_size: 64
